# norm_rows fast path for plain PREP modes: all 8 rows of a wave loaded up front, rsq + packed mul + cvt_pk_bf16
# speedup vs baseline: 1.1157x; 1.0038x over previous
; #define INP(i) ((const float*)(const __attribute__((address_space(1))) float*)PT[(i)])
; __device__ __forceinline__ void norm_rows(const float* src, float* cpy, const float* g, bf16_t* out, int mode, int gw, int ngw, int lane) {
;     ...
;   if (mode == 4) { if (gw == 0) { unsigned zz = 0u; asm volatile("" : "+v"(zz)); for (int j = 0; j < 4; ++j) ((u32x4*)(out - 2048))[lane + 64 * j] = (u32x4){zz, zz, zz, zz}; } mode = 0; }
;   f32x4 vn[2][4];
;   if (gw < M) {
; __global__ void __launch_bounds__(512, 2) mega_fwd(KArgs args) {
;     ...
;       case K_PREP: { TIDS;
;         if (d.lda == 1) norm_rows(INP(0), X, INP(d.K), (bf16_t*)(ws + d.a), 1, gw, ngw, lane);
;         else norm_rows(X, nullptr, INP(d.K), (bf16_t*)(ws + d.a), d.lda, gw, ngw, lane);
.LBB0_781:
	s_cmpk_lg_i32 s26, 0x800
	s_cbranch_scc1 .Lnr_general
	s_cmp_eq_u32 s12, 0
	s_cbranch_scc1 .Lnr_fast
	s_cmp_eq_u32 s12, 4
	s_cbranch_scc1 .Lnr_fast

; __device__ __forceinline__ unsigned pk2(float lo, float hi) { return f2bf(lo) | (f2bf(hi) << 16); }
; __device__ __forceinline__ void norm_rows(const float* src, float* cpy, const float* g, bf16_t* out, int mode, int gw, int ngw, int lane) {
;     ...
;     for (int j = 0; j < 4; ++j) { vn[0][j] = ((const f32x4*)(src + (size_t)gw * D))[lane + 64 * j]; vn[1][j] = (gw + ngw < M) ? ((const f32x4*)(src + (size_t)(gw + ngw) * D))[lane + 64 * j] : (f32x4){0.f, 0.f, 0.f, 0.f}; }
;   }
;   for (int m0 = gw; m0 < M; m0 += 2 * ngw) {
;     const int m1 = m0 + ngw;
;     const bool has1 = m1 < M;
;     f32x4 v[2][4]; float ss0 = 0.f, ss1 = 0.f;
; #pragma unroll
;     for (int j = 0; j < 4; ++j) { v[0][j] = vn[0][j]; v[1][j] = vn[1][j]; }
;     { const int n0 = m0 + 2 * ngw, n1 = n0 + ngw;
;       if (n0 < M) {
; #pragma unroll
;         for (int j = 0; j < 4; ++j) { vn[0][j] = ((const f32x4*)(src + (size_t)n0 * D))[lane + 64 * j]; vn[1][j] = (n1 < M) ? ((const f32x4*)(src + (size_t)n1 * D))[lane + 64 * j] : (f32x4){0.f, 0.f, 0.f, 0.f}; }
;       } }
; #pragma unroll
;     for (int j = 0; j < 4; ++j) { ss0 += (v[0][j].x * v[0][j].x + v[0][j].y * v[0][j].y) + (v[0][j].z * v[0][j].z + v[0][j].w * v[0][j].w);
;       ss1 += (v[1][j].x * v[1][j].x + v[1][j].y * v[1][j].y) + (v[1][j].z * v[1][j].z + v[1][j].w * v[1][j].w); }
;     ss0 = wave_total_n(ss0); ss1 = wave_total_n(ss1);
; #pragma unroll
;     for (int rr = 0; rr < 2; ++rr) {
;       if (rr == 1 && !has1) break;
;       const int m = rr ? m1 : m0; const float rs = 1.0f / sqrtf((rr ? ss1 : ss0) * (1.f / D) + 1e-6f);
; #pragma unroll
;       for (int j = 0; j < 4; ++j) {
;         const f32x4 y = v[rr][j] * rs * gg[j];
;         if (mode == 3) { ((f32x4*)(cpy + (size_t)m * D))[lane + 64 * j] = y; }
;         else {
;           if (mode == 1) ((f32x4*)(cpy + (size_t)m * D))[lane + 64 * j] = v[rr][j];
;           u32x2 w; w.x = pk2(y.x, y.y); w.y = pk2(y.z, y.w);
;           if (mode == 2) {
;             *(u32x2*)(out + (size_t)m * 2048 + 4 * (lane + 64 * j)) = w;
;             if (m + 1 < M) *(u32x2*)(out + (size_t)(m + 1) * 2048 + 1024 + 4 * (lane + 64 * j)) = w;
;             if (m == 0) { unsigned zz = 0u; asm volatile("" : "+v"(zz)); *(u32x2*)(out + 1024 + 4 * (lane + 64 * j)) = (u32x2){zz, zz}; }
;           } else *(u32x2*)(out + (size_t)m * 1024 + 4 * (lane + 64 * j)) = w;
.Lnr_fast:
	v_lshlrev_b32_e32 v146, 3, v92
	v_readlane_b32 s100, v254, 29
	v_readlane_b32 s101, v254, 30
	s_lshl_b32 s4, s6, 12
	s_nop 0
	s_add_u32 s100, s100, s4
	s_addc_u32 s101, s101, 0
	global_load_dwordx4 v[18:21], v0, s[100:101]
	global_load_dwordx4 v[22:25], v0, s[100:101] offset:1024
	global_load_dwordx4 v[26:29], v0, s[100:101] offset:2048
	global_load_dwordx4 v[30:33], v0, s[100:101] offset:3072
	s_add_u32 s100, s100, 0x800000
	s_addc_u32 s101, s101, 0
	global_load_dwordx4 v[34:37], v0, s[100:101]
	global_load_dwordx4 v[38:41], v0, s[100:101] offset:1024
	global_load_dwordx4 v[42:45], v0, s[100:101] offset:2048
	global_load_dwordx4 v[46:49], v0, s[100:101] offset:3072
	s_add_u32 s100, s100, 0x800000
	s_addc_u32 s101, s101, 0
	global_load_dwordx4 v[50:53], v0, s[100:101]
	global_load_dwordx4 v[54:57], v0, s[100:101] offset:1024
	global_load_dwordx4 v[58:61], v0, s[100:101] offset:2048
	global_load_dwordx4 v[62:65], v0, s[100:101] offset:3072
	s_add_u32 s100, s100, 0x800000
	s_addc_u32 s101, s101, 0
	global_load_dwordx4 v[66:69], v0, s[100:101]
	global_load_dwordx4 v[70:73], v0, s[100:101] offset:1024
	global_load_dwordx4 v[74:77], v0, s[100:101] offset:2048
	global_load_dwordx4 v[78:81], v0, s[100:101] offset:3072
	s_add_u32 s100, s100, 0x800000
	s_addc_u32 s101, s101, 0
	global_load_dwordx4 v[82:85], v0, s[100:101]
	global_load_dwordx4 v[86:89], v0, s[100:101] offset:1024
	global_load_dwordx4 v[90:93], v0, s[100:101] offset:2048
	global_load_dwordx4 v[94:97], v0, s[100:101] offset:3072
	s_add_u32 s100, s100, 0x800000
	s_addc_u32 s101, s101, 0
	global_load_dwordx4 v[98:101], v0, s[100:101]
	global_load_dwordx4 v[102:105], v0, s[100:101] offset:1024
	global_load_dwordx4 v[106:109], v0, s[100:101] offset:2048
	global_load_dwordx4 v[110:113], v0, s[100:101] offset:3072
	s_add_u32 s100, s100, 0x800000
	s_addc_u32 s101, s101, 0
	global_load_dwordx4 v[114:117], v0, s[100:101]
	global_load_dwordx4 v[118:121], v0, s[100:101] offset:1024
	global_load_dwordx4 v[122:125], v0, s[100:101] offset:2048
	global_load_dwordx4 v[126:129], v0, s[100:101] offset:3072
	s_add_u32 s100, s100, 0x800000
	s_addc_u32 s101, s101, 0
	global_load_dwordx4 v[130:133], v0, s[100:101]
	global_load_dwordx4 v[134:137], v0, s[100:101] offset:1024
	global_load_dwordx4 v[138:141], v0, s[100:101] offset:2048
	global_load_dwordx4 v[142:145], v0, s[100:101] offset:3072
	s_add_u32 s100, s100, 0x800000
	s_addc_u32 s101, s101, 0
	s_lshl_b32 s4, s6, 11
	s_add_u32 s100, s8, s4
	s_addc_u32 s101, s9, 0
	s_waitcnt vmcnt(28)
	v_mul_f32_e32 v147, v18, v18
	v_mul_f32_e32 v148, v19, v19
	v_fmac_f32_e32 v147, v20, v20
	v_fmac_f32_e32 v148, v21, v21
	v_fmac_f32_e32 v147, v22, v22
	v_fmac_f32_e32 v148, v23, v23
	v_fmac_f32_e32 v147, v24, v24
	v_fmac_f32_e32 v148, v25, v25
	v_fmac_f32_e32 v147, v26, v26
	v_fmac_f32_e32 v148, v27, v27
	v_fmac_f32_e32 v147, v28, v28
	v_fmac_f32_e32 v148, v29, v29
	v_fmac_f32_e32 v147, v30, v30
	v_fmac_f32_e32 v148, v31, v31
	v_fmac_f32_e32 v147, v32, v32
	v_fmac_f32_e32 v148, v33, v33
	v_add_f32_e32 v147, v147, v148
	s_nop 1
	v_add_f32_dpp v147, v147, v147 row_shr:1 row_mask:0xf bank_mask:0xf bound_ctrl:1
	s_nop 1
	v_add_f32_dpp v147, v147, v147 row_shr:2 row_mask:0xf bank_mask:0xf bound_ctrl:1
	s_nop 1
	v_add_f32_dpp v147, v147, v147 row_shr:4 row_mask:0xf bank_mask:0xf bound_ctrl:1
	s_nop 1
	v_add_f32_dpp v147, v147, v147 row_shr:8 row_mask:0xf bank_mask:0xf bound_ctrl:1
	v_mov_b32_e32 v148, v1
	s_nop 1
	v_mov_b32_dpp v148, v147 row_bcast:15 row_mask:0xa bank_mask:0xf
	v_add_f32_e32 v147, v147, v148
	v_mov_b32_e32 v148, v1
	s_nop 1
	v_mov_b32_dpp v148, v147 row_bcast:31 row_mask:0xc bank_mask:0xf
	v_add_f32_e32 v147, v147, v148
	s_nop 1
	v_readlane_b32 s4, v147, 63
	s_nop 3
	v_fma_f32 v148, s4, v178, v205
	v_rsq_f32_e32 v148, v148
	s_nop 0
	v_mov_b32_e32 v149, v148
	v_pk_mul_f32 v[18:19], v[18:19], v[148:149]
	v_pk_mul_f32 v[20:21], v[20:21], v[148:149]
	v_pk_mul_f32 v[18:19], v[18:19], v[2:3]
	v_pk_mul_f32 v[20:21], v[20:21], v[4:5]
	v_cvt_pk_bf16_f32 v18, v18, v19
	v_cvt_pk_bf16_f32 v19, v20, v21
	global_store_dwordx2 v146, v[18:19], s[100:101]
	v_pk_mul_f32 v[22:23], v[22:23], v[148:149]
	v_pk_mul_f32 v[24:25], v[24:25], v[148:149]
	v_pk_mul_f32 v[22:23], v[22:23], v[6:7]
	v_pk_mul_f32 v[24:25], v[24:25], v[8:9]
	v_cvt_pk_bf16_f32 v22, v22, v23
	v_cvt_pk_bf16_f32 v23, v24, v25
	global_store_dwordx2 v146, v[22:23], s[100:101] offset:512
	v_pk_mul_f32 v[26:27], v[26:27], v[148:149]
	v_pk_mul_f32 v[28:29], v[28:29], v[148:149]
	v_pk_mul_f32 v[26:27], v[26:27], v[10:11]
	v_pk_mul_f32 v[28:29], v[28:29], v[12:13]
	v_cvt_pk_bf16_f32 v26, v26, v27
	v_cvt_pk_bf16_f32 v27, v28, v29
	global_store_dwordx2 v146, v[26:27], s[100:101] offset:1024
	v_pk_mul_f32 v[30:31], v[30:31], v[148:149]
	v_pk_mul_f32 v[32:33], v[32:33], v[148:149]
	v_pk_mul_f32 v[30:31], v[30:31], v[14:15]
	v_pk_mul_f32 v[32:33], v[32:33], v[16:17]
	v_cvt_pk_bf16_f32 v30, v30, v31
	v_cvt_pk_bf16_f32 v31, v32, v33
	global_store_dwordx2 v146, v[30:31], s[100:101] offset:1536
	s_add_u32 s100, s100, 0x400000
	s_addc_u32 s101, s101, 0
	s_waitcnt vmcnt(28)
; __device__ __forceinline__ unsigned pk2(float lo, float hi) { return f2bf(lo) | (f2bf(hi) << 16); }
; __device__ __forceinline__ void norm_rows(const float* src, float* cpy, const float* g, bf16_t* out, int mode, int gw, int ngw, int lane) {
;     ...
;     for (int j = 0; j < 4; ++j) { ss0 += (v[0][j].x * v[0][j].x + v[0][j].y * v[0][j].y) + (v[0][j].z * v[0][j].z + v[0][j].w * v[0][j].w);
;       ss1 += (v[1][j].x * v[1][j].x + v[1][j].y * v[1][j].y) + (v[1][j].z * v[1][j].z + v[1][j].w * v[1][j].w); }
;     ss0 = wave_total_n(ss0); ss1 = wave_total_n(ss1);
; #pragma unroll
;     for (int rr = 0; rr < 2; ++rr) {
;       if (rr == 1 && !has1) break;
;       const int m = rr ? m1 : m0; const float rs = 1.0f / sqrtf((rr ? ss1 : ss0) * (1.f / D) + 1e-6f);
; #pragma unroll
;       for (int j = 0; j < 4; ++j) {
;         const f32x4 y = v[rr][j] * rs * gg[j];
;         if (mode == 3) { ((f32x4*)(cpy + (size_t)m * D))[lane + 64 * j] = y; }
;         else {
;           if (mode == 1) ((f32x4*)(cpy + (size_t)m * D))[lane + 64 * j] = v[rr][j];
;           u32x2 w; w.x = pk2(y.x, y.y); w.y = pk2(y.z, y.w);
;           if (mode == 2) {
;             *(u32x2*)(out + (size_t)m * 2048 + 4 * (lane + 64 * j)) = w;
;             if (m + 1 < M) *(u32x2*)(out + (size_t)(m + 1) * 2048 + 1024 + 4 * (lane + 64 * j)) = w;
;             if (m == 0) { unsigned zz = 0u; asm volatile("" : "+v"(zz)); *(u32x2*)(out + 1024 + 4 * (lane + 64 * j)) = (u32x2){zz, zz}; }
;           } else *(u32x2*)(out + (size_t)m * 1024 + 4 * (lane + 64 * j)) = w;
	v_mul_f32_e32 v147, v34, v34
	v_mul_f32_e32 v148, v35, v35
	v_fmac_f32_e32 v147, v36, v36
	v_fmac_f32_e32 v148, v37, v37
	v_fmac_f32_e32 v147, v38, v38
	v_fmac_f32_e32 v148, v39, v39
	v_fmac_f32_e32 v147, v40, v40
	v_fmac_f32_e32 v148, v41, v41
	v_fmac_f32_e32 v147, v42, v42
	v_fmac_f32_e32 v148, v43, v43
	v_fmac_f32_e32 v147, v44, v44
	v_fmac_f32_e32 v148, v45, v45
	v_fmac_f32_e32 v147, v46, v46
	v_fmac_f32_e32 v148, v47, v47
	v_fmac_f32_e32 v147, v48, v48
	v_fmac_f32_e32 v148, v49, v49
	v_add_f32_e32 v147, v147, v148
	s_nop 1
	v_add_f32_dpp v147, v147, v147 row_shr:1 row_mask:0xf bank_mask:0xf bound_ctrl:1
	s_nop 1
	v_add_f32_dpp v147, v147, v147 row_shr:2 row_mask:0xf bank_mask:0xf bound_ctrl:1
	s_nop 1
	v_add_f32_dpp v147, v147, v147 row_shr:4 row_mask:0xf bank_mask:0xf bound_ctrl:1
	s_nop 1
	v_add_f32_dpp v147, v147, v147 row_shr:8 row_mask:0xf bank_mask:0xf bound_ctrl:1
	v_mov_b32_e32 v148, v1
	s_nop 1
	v_mov_b32_dpp v148, v147 row_bcast:15 row_mask:0xa bank_mask:0xf
	v_add_f32_e32 v147, v147, v148
	v_mov_b32_e32 v148, v1
	s_nop 1
	v_mov_b32_dpp v148, v147 row_bcast:31 row_mask:0xc bank_mask:0xf
	v_add_f32_e32 v147, v147, v148
	s_nop 1
	v_readlane_b32 s4, v147, 63
	s_nop 3
	v_fma_f32 v148, s4, v178, v205
	v_rsq_f32_e32 v148, v148
	s_nop 0
	v_mov_b32_e32 v149, v148
	v_pk_mul_f32 v[34:35], v[34:35], v[148:149]
	v_pk_mul_f32 v[36:37], v[36:37], v[148:149]
	v_pk_mul_f32 v[34:35], v[34:35], v[2:3]
	v_pk_mul_f32 v[36:37], v[36:37], v[4:5]
	v_cvt_pk_bf16_f32 v34, v34, v35
	v_cvt_pk_bf16_f32 v35, v36, v37
	global_store_dwordx2 v146, v[34:35], s[100:101]
	v_pk_mul_f32 v[38:39], v[38:39], v[148:149]
	v_pk_mul_f32 v[40:41], v[40:41], v[148:149]
	v_pk_mul_f32 v[38:39], v[38:39], v[6:7]
	v_pk_mul_f32 v[40:41], v[40:41], v[8:9]
	v_cvt_pk_bf16_f32 v38, v38, v39
	v_cvt_pk_bf16_f32 v39, v40, v41
	global_store_dwordx2 v146, v[38:39], s[100:101] offset:512
	v_pk_mul_f32 v[42:43], v[42:43], v[148:149]
	v_pk_mul_f32 v[44:45], v[44:45], v[148:149]
	v_pk_mul_f32 v[42:43], v[42:43], v[10:11]
	v_pk_mul_f32 v[44:45], v[44:45], v[12:13]
	v_cvt_pk_bf16_f32 v42, v42, v43
	v_cvt_pk_bf16_f32 v43, v44, v45
	global_store_dwordx2 v146, v[42:43], s[100:101] offset:1024
	v_pk_mul_f32 v[46:47], v[46:47], v[148:149]
	v_pk_mul_f32 v[48:49], v[48:49], v[148:149]
	v_pk_mul_f32 v[46:47], v[46:47], v[14:15]
	v_pk_mul_f32 v[48:49], v[48:49], v[16:17]
	v_cvt_pk_bf16_f32 v46, v46, v47
	v_cvt_pk_bf16_f32 v47, v48, v49
	global_store_dwordx2 v146, v[46:47], s[100:101] offset:1536
	s_add_u32 s100, s100, 0x400000
	s_addc_u32 s101, s101, 0
	s_waitcnt vmcnt(28)
	v_mul_f32_e32 v147, v50, v50
	v_mul_f32_e32 v148, v51, v51
	v_fmac_f32_e32 v147, v52, v52
	v_fmac_f32_e32 v148, v53, v53
	v_fmac_f32_e32 v147, v54, v54
	v_fmac_f32_e32 v148, v55, v55
	v_fmac_f32_e32 v147, v56, v56
	v_fmac_f32_e32 v148, v57, v57
	v_fmac_f32_e32 v147, v58, v58
	v_fmac_f32_e32 v148, v59, v59
	v_fmac_f32_e32 v147, v60, v60
	v_fmac_f32_e32 v148, v61, v61
	v_fmac_f32_e32 v147, v62, v62
	v_fmac_f32_e32 v148, v63, v63
	v_fmac_f32_e32 v147, v64, v64
	v_fmac_f32_e32 v148, v65, v65
	v_add_f32_e32 v147, v147, v148
	s_nop 1
	v_add_f32_dpp v147, v147, v147 row_shr:1 row_mask:0xf bank_mask:0xf bound_ctrl:1
	s_nop 1
	v_add_f32_dpp v147, v147, v147 row_shr:2 row_mask:0xf bank_mask:0xf bound_ctrl:1
	s_nop 1
	v_add_f32_dpp v147, v147, v147 row_shr:4 row_mask:0xf bank_mask:0xf bound_ctrl:1
	s_nop 1
	v_add_f32_dpp v147, v147, v147 row_shr:8 row_mask:0xf bank_mask:0xf bound_ctrl:1
	v_mov_b32_e32 v148, v1
	s_nop 1
	v_mov_b32_dpp v148, v147 row_bcast:15 row_mask:0xa bank_mask:0xf
	v_add_f32_e32 v147, v147, v148
	v_mov_b32_e32 v148, v1
	s_nop 1
	v_mov_b32_dpp v148, v147 row_bcast:31 row_mask:0xc bank_mask:0xf
	v_add_f32_e32 v147, v147, v148
	s_nop 1
	v_readlane_b32 s4, v147, 63
	s_nop 3
	v_fma_f32 v148, s4, v178, v205
	v_rsq_f32_e32 v148, v148
	s_nop 0
	v_mov_b32_e32 v149, v148
	v_pk_mul_f32 v[50:51], v[50:51], v[148:149]
	v_pk_mul_f32 v[52:53], v[52:53], v[148:149]
	v_pk_mul_f32 v[50:51], v[50:51], v[2:3]
	v_pk_mul_f32 v[52:53], v[52:53], v[4:5]
	v_cvt_pk_bf16_f32 v50, v50, v51
	v_cvt_pk_bf16_f32 v51, v52, v53
	global_store_dwordx2 v146, v[50:51], s[100:101]
	v_pk_mul_f32 v[54:55], v[54:55], v[148:149]
	v_pk_mul_f32 v[56:57], v[56:57], v[148:149]
	v_pk_mul_f32 v[54:55], v[54:55], v[6:7]
	v_pk_mul_f32 v[56:57], v[56:57], v[8:9]
	v_cvt_pk_bf16_f32 v54, v54, v55
	v_cvt_pk_bf16_f32 v55, v56, v57
	global_store_dwordx2 v146, v[54:55], s[100:101] offset:512
	v_pk_mul_f32 v[58:59], v[58:59], v[148:149]
	v_pk_mul_f32 v[60:61], v[60:61], v[148:149]
	v_pk_mul_f32 v[58:59], v[58:59], v[10:11]
	v_pk_mul_f32 v[60:61], v[60:61], v[12:13]
	v_cvt_pk_bf16_f32 v58, v58, v59
	v_cvt_pk_bf16_f32 v59, v60, v61
	global_store_dwordx2 v146, v[58:59], s[100:101] offset:1024
	v_pk_mul_f32 v[62:63], v[62:63], v[148:149]
	v_pk_mul_f32 v[64:65], v[64:65], v[148:149]
	v_pk_mul_f32 v[62:63], v[62:63], v[14:15]
	v_pk_mul_f32 v[64:65], v[64:65], v[16:17]
	v_cvt_pk_bf16_f32 v62, v62, v63
	v_cvt_pk_bf16_f32 v63, v64, v65
	global_store_dwordx2 v146, v[62:63], s[100:101] offset:1536
	s_add_u32 s100, s100, 0x400000
	s_addc_u32 s101, s101, 0
	s_waitcnt vmcnt(28)
; __device__ __forceinline__ unsigned pk2(float lo, float hi) { return f2bf(lo) | (f2bf(hi) << 16); }
; __device__ __forceinline__ void norm_rows(const float* src, float* cpy, const float* g, bf16_t* out, int mode, int gw, int ngw, int lane) {
;     ...
;     for (int j = 0; j < 4; ++j) { ss0 += (v[0][j].x * v[0][j].x + v[0][j].y * v[0][j].y) + (v[0][j].z * v[0][j].z + v[0][j].w * v[0][j].w);
;       ss1 += (v[1][j].x * v[1][j].x + v[1][j].y * v[1][j].y) + (v[1][j].z * v[1][j].z + v[1][j].w * v[1][j].w); }
;     ss0 = wave_total_n(ss0); ss1 = wave_total_n(ss1);
; #pragma unroll
;     for (int rr = 0; rr < 2; ++rr) {
;       if (rr == 1 && !has1) break;
;       const int m = rr ? m1 : m0; const float rs = 1.0f / sqrtf((rr ? ss1 : ss0) * (1.f / D) + 1e-6f);
; #pragma unroll
;       for (int j = 0; j < 4; ++j) {
;         const f32x4 y = v[rr][j] * rs * gg[j];
;         if (mode == 3) { ((f32x4*)(cpy + (size_t)m * D))[lane + 64 * j] = y; }
;         else {
;           if (mode == 1) ((f32x4*)(cpy + (size_t)m * D))[lane + 64 * j] = v[rr][j];
;           u32x2 w; w.x = pk2(y.x, y.y); w.y = pk2(y.z, y.w);
;           if (mode == 2) {
;             *(u32x2*)(out + (size_t)m * 2048 + 4 * (lane + 64 * j)) = w;
;             if (m + 1 < M) *(u32x2*)(out + (size_t)(m + 1) * 2048 + 1024 + 4 * (lane + 64 * j)) = w;
;             if (m == 0) { unsigned zz = 0u; asm volatile("" : "+v"(zz)); *(u32x2*)(out + 1024 + 4 * (lane + 64 * j)) = (u32x2){zz, zz}; }
;           } else *(u32x2*)(out + (size_t)m * 1024 + 4 * (lane + 64 * j)) = w;
	v_mul_f32_e32 v147, v66, v66
	v_mul_f32_e32 v148, v67, v67
	v_fmac_f32_e32 v147, v68, v68
	v_fmac_f32_e32 v148, v69, v69
	v_fmac_f32_e32 v147, v70, v70
	v_fmac_f32_e32 v148, v71, v71
	v_fmac_f32_e32 v147, v72, v72
	v_fmac_f32_e32 v148, v73, v73
	v_fmac_f32_e32 v147, v74, v74
	v_fmac_f32_e32 v148, v75, v75
	v_fmac_f32_e32 v147, v76, v76
	v_fmac_f32_e32 v148, v77, v77
	v_fmac_f32_e32 v147, v78, v78
	v_fmac_f32_e32 v148, v79, v79
	v_fmac_f32_e32 v147, v80, v80
	v_fmac_f32_e32 v148, v81, v81
	v_add_f32_e32 v147, v147, v148
	s_nop 1
	v_add_f32_dpp v147, v147, v147 row_shr:1 row_mask:0xf bank_mask:0xf bound_ctrl:1
	s_nop 1
	v_add_f32_dpp v147, v147, v147 row_shr:2 row_mask:0xf bank_mask:0xf bound_ctrl:1
	s_nop 1
	v_add_f32_dpp v147, v147, v147 row_shr:4 row_mask:0xf bank_mask:0xf bound_ctrl:1
	s_nop 1
	v_add_f32_dpp v147, v147, v147 row_shr:8 row_mask:0xf bank_mask:0xf bound_ctrl:1
	v_mov_b32_e32 v148, v1
	s_nop 1
	v_mov_b32_dpp v148, v147 row_bcast:15 row_mask:0xa bank_mask:0xf
	v_add_f32_e32 v147, v147, v148
	v_mov_b32_e32 v148, v1
	s_nop 1
	v_mov_b32_dpp v148, v147 row_bcast:31 row_mask:0xc bank_mask:0xf
	v_add_f32_e32 v147, v147, v148
	s_nop 1
	v_readlane_b32 s4, v147, 63
	s_nop 3
	v_fma_f32 v148, s4, v178, v205
	v_rsq_f32_e32 v148, v148
	s_nop 0
	v_mov_b32_e32 v149, v148
	v_pk_mul_f32 v[66:67], v[66:67], v[148:149]
	v_pk_mul_f32 v[68:69], v[68:69], v[148:149]
	v_pk_mul_f32 v[66:67], v[66:67], v[2:3]
	v_pk_mul_f32 v[68:69], v[68:69], v[4:5]
	v_cvt_pk_bf16_f32 v66, v66, v67
	v_cvt_pk_bf16_f32 v67, v68, v69
	global_store_dwordx2 v146, v[66:67], s[100:101]
	v_pk_mul_f32 v[70:71], v[70:71], v[148:149]
	v_pk_mul_f32 v[72:73], v[72:73], v[148:149]
	v_pk_mul_f32 v[70:71], v[70:71], v[6:7]
	v_pk_mul_f32 v[72:73], v[72:73], v[8:9]
	v_cvt_pk_bf16_f32 v70, v70, v71
	v_cvt_pk_bf16_f32 v71, v72, v73
	global_store_dwordx2 v146, v[70:71], s[100:101] offset:512
	v_pk_mul_f32 v[74:75], v[74:75], v[148:149]
	v_pk_mul_f32 v[76:77], v[76:77], v[148:149]
	v_pk_mul_f32 v[74:75], v[74:75], v[10:11]
	v_pk_mul_f32 v[76:77], v[76:77], v[12:13]
	v_cvt_pk_bf16_f32 v74, v74, v75
	v_cvt_pk_bf16_f32 v75, v76, v77
	global_store_dwordx2 v146, v[74:75], s[100:101] offset:1024
	v_pk_mul_f32 v[78:79], v[78:79], v[148:149]
	v_pk_mul_f32 v[80:81], v[80:81], v[148:149]
	v_pk_mul_f32 v[78:79], v[78:79], v[14:15]
	v_pk_mul_f32 v[80:81], v[80:81], v[16:17]
	v_cvt_pk_bf16_f32 v78, v78, v79
	v_cvt_pk_bf16_f32 v79, v80, v81
	global_store_dwordx2 v146, v[78:79], s[100:101] offset:1536
	s_add_u32 s100, s100, 0x400000
	s_addc_u32 s101, s101, 0
	s_waitcnt vmcnt(28)
	v_mul_f32_e32 v147, v82, v82
	v_mul_f32_e32 v148, v83, v83
	v_fmac_f32_e32 v147, v84, v84
	v_fmac_f32_e32 v148, v85, v85
	v_fmac_f32_e32 v147, v86, v86
	v_fmac_f32_e32 v148, v87, v87
	v_fmac_f32_e32 v147, v88, v88
	v_fmac_f32_e32 v148, v89, v89
	v_fmac_f32_e32 v147, v90, v90
	v_fmac_f32_e32 v148, v91, v91
	v_fmac_f32_e32 v147, v92, v92
	v_fmac_f32_e32 v148, v93, v93
	v_fmac_f32_e32 v147, v94, v94
	v_fmac_f32_e32 v148, v95, v95
	v_fmac_f32_e32 v147, v96, v96
	v_fmac_f32_e32 v148, v97, v97
	v_add_f32_e32 v147, v147, v148
	s_nop 1
	v_add_f32_dpp v147, v147, v147 row_shr:1 row_mask:0xf bank_mask:0xf bound_ctrl:1
	s_nop 1
	v_add_f32_dpp v147, v147, v147 row_shr:2 row_mask:0xf bank_mask:0xf bound_ctrl:1
	s_nop 1
	v_add_f32_dpp v147, v147, v147 row_shr:4 row_mask:0xf bank_mask:0xf bound_ctrl:1
	s_nop 1
	v_add_f32_dpp v147, v147, v147 row_shr:8 row_mask:0xf bank_mask:0xf bound_ctrl:1
	v_mov_b32_e32 v148, v1
	s_nop 1
	v_mov_b32_dpp v148, v147 row_bcast:15 row_mask:0xa bank_mask:0xf
	v_add_f32_e32 v147, v147, v148
	v_mov_b32_e32 v148, v1
	s_nop 1
	v_mov_b32_dpp v148, v147 row_bcast:31 row_mask:0xc bank_mask:0xf
	v_add_f32_e32 v147, v147, v148
	s_nop 1
	v_readlane_b32 s4, v147, 63
	s_nop 3
	v_fma_f32 v148, s4, v178, v205
	v_rsq_f32_e32 v148, v148
	s_nop 0
	v_mov_b32_e32 v149, v148
	v_pk_mul_f32 v[82:83], v[82:83], v[148:149]
	v_pk_mul_f32 v[84:85], v[84:85], v[148:149]
	v_pk_mul_f32 v[82:83], v[82:83], v[2:3]
	v_pk_mul_f32 v[84:85], v[84:85], v[4:5]
	v_cvt_pk_bf16_f32 v82, v82, v83
	v_cvt_pk_bf16_f32 v83, v84, v85
	global_store_dwordx2 v146, v[82:83], s[100:101]
	v_pk_mul_f32 v[86:87], v[86:87], v[148:149]
	v_pk_mul_f32 v[88:89], v[88:89], v[148:149]
	v_pk_mul_f32 v[86:87], v[86:87], v[6:7]
	v_pk_mul_f32 v[88:89], v[88:89], v[8:9]
	v_cvt_pk_bf16_f32 v86, v86, v87
	v_cvt_pk_bf16_f32 v87, v88, v89
	global_store_dwordx2 v146, v[86:87], s[100:101] offset:512
	v_pk_mul_f32 v[90:91], v[90:91], v[148:149]
	v_pk_mul_f32 v[92:93], v[92:93], v[148:149]
	v_pk_mul_f32 v[90:91], v[90:91], v[10:11]
	v_pk_mul_f32 v[92:93], v[92:93], v[12:13]
	v_cvt_pk_bf16_f32 v90, v90, v91
	v_cvt_pk_bf16_f32 v91, v92, v93
	global_store_dwordx2 v146, v[90:91], s[100:101] offset:1024
	v_pk_mul_f32 v[94:95], v[94:95], v[148:149]
	v_pk_mul_f32 v[96:97], v[96:97], v[148:149]
	v_pk_mul_f32 v[94:95], v[94:95], v[14:15]
	v_pk_mul_f32 v[96:97], v[96:97], v[16:17]
	v_cvt_pk_bf16_f32 v94, v94, v95
	v_cvt_pk_bf16_f32 v95, v96, v97
	global_store_dwordx2 v146, v[94:95], s[100:101] offset:1536
	s_add_u32 s100, s100, 0x400000
	s_addc_u32 s101, s101, 0
	s_waitcnt vmcnt(28)
; __device__ __forceinline__ unsigned pk2(float lo, float hi) { return f2bf(lo) | (f2bf(hi) << 16); }
; __device__ __forceinline__ void norm_rows(const float* src, float* cpy, const float* g, bf16_t* out, int mode, int gw, int ngw, int lane) {
;     ...
;     for (int j = 0; j < 4; ++j) { ss0 += (v[0][j].x * v[0][j].x + v[0][j].y * v[0][j].y) + (v[0][j].z * v[0][j].z + v[0][j].w * v[0][j].w);
;       ss1 += (v[1][j].x * v[1][j].x + v[1][j].y * v[1][j].y) + (v[1][j].z * v[1][j].z + v[1][j].w * v[1][j].w); }
;     ss0 = wave_total_n(ss0); ss1 = wave_total_n(ss1);
; #pragma unroll
;     for (int rr = 0; rr < 2; ++rr) {
;       if (rr == 1 && !has1) break;
;       const int m = rr ? m1 : m0; const float rs = 1.0f / sqrtf((rr ? ss1 : ss0) * (1.f / D) + 1e-6f);
; #pragma unroll
;       for (int j = 0; j < 4; ++j) {
;         const f32x4 y = v[rr][j] * rs * gg[j];
;         if (mode == 3) { ((f32x4*)(cpy + (size_t)m * D))[lane + 64 * j] = y; }
;         else {
;           if (mode == 1) ((f32x4*)(cpy + (size_t)m * D))[lane + 64 * j] = v[rr][j];
;           u32x2 w; w.x = pk2(y.x, y.y); w.y = pk2(y.z, y.w);
;           if (mode == 2) {
;             *(u32x2*)(out + (size_t)m * 2048 + 4 * (lane + 64 * j)) = w;
;             if (m + 1 < M) *(u32x2*)(out + (size_t)(m + 1) * 2048 + 1024 + 4 * (lane + 64 * j)) = w;
;             if (m == 0) { unsigned zz = 0u; asm volatile("" : "+v"(zz)); *(u32x2*)(out + 1024 + 4 * (lane + 64 * j)) = (u32x2){zz, zz}; }
;           } else *(u32x2*)(out + (size_t)m * 1024 + 4 * (lane + 64 * j)) = w;
	v_mul_f32_e32 v147, v98, v98
	v_mul_f32_e32 v148, v99, v99
	v_fmac_f32_e32 v147, v100, v100
	v_fmac_f32_e32 v148, v101, v101
	v_fmac_f32_e32 v147, v102, v102
	v_fmac_f32_e32 v148, v103, v103
	v_fmac_f32_e32 v147, v104, v104
	v_fmac_f32_e32 v148, v105, v105
	v_fmac_f32_e32 v147, v106, v106
	v_fmac_f32_e32 v148, v107, v107
	v_fmac_f32_e32 v147, v108, v108
	v_fmac_f32_e32 v148, v109, v109
	v_fmac_f32_e32 v147, v110, v110
	v_fmac_f32_e32 v148, v111, v111
	v_fmac_f32_e32 v147, v112, v112
	v_fmac_f32_e32 v148, v113, v113
	v_add_f32_e32 v147, v147, v148
	s_nop 1
	v_add_f32_dpp v147, v147, v147 row_shr:1 row_mask:0xf bank_mask:0xf bound_ctrl:1
	s_nop 1
	v_add_f32_dpp v147, v147, v147 row_shr:2 row_mask:0xf bank_mask:0xf bound_ctrl:1
	s_nop 1
	v_add_f32_dpp v147, v147, v147 row_shr:4 row_mask:0xf bank_mask:0xf bound_ctrl:1
	s_nop 1
	v_add_f32_dpp v147, v147, v147 row_shr:8 row_mask:0xf bank_mask:0xf bound_ctrl:1
	v_mov_b32_e32 v148, v1
	s_nop 1
	v_mov_b32_dpp v148, v147 row_bcast:15 row_mask:0xa bank_mask:0xf
	v_add_f32_e32 v147, v147, v148
	v_mov_b32_e32 v148, v1
	s_nop 1
	v_mov_b32_dpp v148, v147 row_bcast:31 row_mask:0xc bank_mask:0xf
	v_add_f32_e32 v147, v147, v148
	s_nop 1
	v_readlane_b32 s4, v147, 63
	s_nop 3
	v_fma_f32 v148, s4, v178, v205
	v_rsq_f32_e32 v148, v148
	s_nop 0
	v_mov_b32_e32 v149, v148
	v_pk_mul_f32 v[98:99], v[98:99], v[148:149]
	v_pk_mul_f32 v[100:101], v[100:101], v[148:149]
	v_pk_mul_f32 v[98:99], v[98:99], v[2:3]
	v_pk_mul_f32 v[100:101], v[100:101], v[4:5]
	v_cvt_pk_bf16_f32 v98, v98, v99
	v_cvt_pk_bf16_f32 v99, v100, v101
	global_store_dwordx2 v146, v[98:99], s[100:101]
	v_pk_mul_f32 v[102:103], v[102:103], v[148:149]
	v_pk_mul_f32 v[104:105], v[104:105], v[148:149]
	v_pk_mul_f32 v[102:103], v[102:103], v[6:7]
	v_pk_mul_f32 v[104:105], v[104:105], v[8:9]
	v_cvt_pk_bf16_f32 v102, v102, v103
	v_cvt_pk_bf16_f32 v103, v104, v105
	global_store_dwordx2 v146, v[102:103], s[100:101] offset:512
	v_pk_mul_f32 v[106:107], v[106:107], v[148:149]
	v_pk_mul_f32 v[108:109], v[108:109], v[148:149]
	v_pk_mul_f32 v[106:107], v[106:107], v[10:11]
	v_pk_mul_f32 v[108:109], v[108:109], v[12:13]
	v_cvt_pk_bf16_f32 v106, v106, v107
	v_cvt_pk_bf16_f32 v107, v108, v109
	global_store_dwordx2 v146, v[106:107], s[100:101] offset:1024
	v_pk_mul_f32 v[110:111], v[110:111], v[148:149]
	v_pk_mul_f32 v[112:113], v[112:113], v[148:149]
	v_pk_mul_f32 v[110:111], v[110:111], v[14:15]
	v_pk_mul_f32 v[112:113], v[112:113], v[16:17]
	v_cvt_pk_bf16_f32 v110, v110, v111
	v_cvt_pk_bf16_f32 v111, v112, v113
	global_store_dwordx2 v146, v[110:111], s[100:101] offset:1536
	s_add_u32 s100, s100, 0x400000
	s_addc_u32 s101, s101, 0
	s_waitcnt vmcnt(28)
; __device__ __forceinline__ unsigned pk2(float lo, float hi) { return f2bf(lo) | (f2bf(hi) << 16); }
; __device__ __forceinline__ void norm_rows(const float* src, float* cpy, const float* g, bf16_t* out, int mode, int gw, int ngw, int lane) {
;     ...
;     for (int j = 0; j < 4; ++j) { ss0 += (v[0][j].x * v[0][j].x + v[0][j].y * v[0][j].y) + (v[0][j].z * v[0][j].z + v[0][j].w * v[0][j].w);
;       ss1 += (v[1][j].x * v[1][j].x + v[1][j].y * v[1][j].y) + (v[1][j].z * v[1][j].z + v[1][j].w * v[1][j].w); }
;     ss0 = wave_total_n(ss0); ss1 = wave_total_n(ss1);
; #pragma unroll
;     for (int rr = 0; rr < 2; ++rr) {
;       if (rr == 1 && !has1) break;
;       const int m = rr ? m1 : m0; const float rs = 1.0f / sqrtf((rr ? ss1 : ss0) * (1.f / D) + 1e-6f);
; #pragma unroll
;       for (int j = 0; j < 4; ++j) {
;         const f32x4 y = v[rr][j] * rs * gg[j];
;         if (mode == 3) { ((f32x4*)(cpy + (size_t)m * D))[lane + 64 * j] = y; }
;         else {
;           if (mode == 1) ((f32x4*)(cpy + (size_t)m * D))[lane + 64 * j] = v[rr][j];
;           u32x2 w; w.x = pk2(y.x, y.y); w.y = pk2(y.z, y.w);
;           if (mode == 2) {
;             *(u32x2*)(out + (size_t)m * 2048 + 4 * (lane + 64 * j)) = w;
;             if (m + 1 < M) *(u32x2*)(out + (size_t)(m + 1) * 2048 + 1024 + 4 * (lane + 64 * j)) = w;
;             if (m == 0) { unsigned zz = 0u; asm volatile("" : "+v"(zz)); *(u32x2*)(out + 1024 + 4 * (lane + 64 * j)) = (u32x2){zz, zz}; }
;           } else *(u32x2*)(out + (size_t)m * 1024 + 4 * (lane + 64 * j)) = w;
	v_mul_f32_e32 v147, v114, v114
	v_mul_f32_e32 v148, v115, v115
	v_fmac_f32_e32 v147, v116, v116
	v_fmac_f32_e32 v148, v117, v117
	v_fmac_f32_e32 v147, v118, v118
	v_fmac_f32_e32 v148, v119, v119
	v_fmac_f32_e32 v147, v120, v120
	v_fmac_f32_e32 v148, v121, v121
	v_fmac_f32_e32 v147, v122, v122
	v_fmac_f32_e32 v148, v123, v123
	v_fmac_f32_e32 v147, v124, v124
	v_fmac_f32_e32 v148, v125, v125
	v_fmac_f32_e32 v147, v126, v126
	v_fmac_f32_e32 v148, v127, v127
	v_fmac_f32_e32 v147, v128, v128
	v_fmac_f32_e32 v148, v129, v129
	v_add_f32_e32 v147, v147, v148
	s_nop 1
	v_add_f32_dpp v147, v147, v147 row_shr:1 row_mask:0xf bank_mask:0xf bound_ctrl:1
	s_nop 1
	v_add_f32_dpp v147, v147, v147 row_shr:2 row_mask:0xf bank_mask:0xf bound_ctrl:1
	s_nop 1
	v_add_f32_dpp v147, v147, v147 row_shr:4 row_mask:0xf bank_mask:0xf bound_ctrl:1
	s_nop 1
	v_add_f32_dpp v147, v147, v147 row_shr:8 row_mask:0xf bank_mask:0xf bound_ctrl:1
	v_mov_b32_e32 v148, v1
	s_nop 1
	v_mov_b32_dpp v148, v147 row_bcast:15 row_mask:0xa bank_mask:0xf
	v_add_f32_e32 v147, v147, v148
	v_mov_b32_e32 v148, v1
	s_nop 1
	v_mov_b32_dpp v148, v147 row_bcast:31 row_mask:0xc bank_mask:0xf
	v_add_f32_e32 v147, v147, v148
	s_nop 1
	v_readlane_b32 s4, v147, 63
	s_nop 3
	v_fma_f32 v148, s4, v178, v205
	v_rsq_f32_e32 v148, v148
	s_nop 0
	v_mov_b32_e32 v149, v148
	v_pk_mul_f32 v[114:115], v[114:115], v[148:149]
	v_pk_mul_f32 v[116:117], v[116:117], v[148:149]
	v_pk_mul_f32 v[114:115], v[114:115], v[2:3]
	v_pk_mul_f32 v[116:117], v[116:117], v[4:5]
	v_cvt_pk_bf16_f32 v114, v114, v115
	v_cvt_pk_bf16_f32 v115, v116, v117
	global_store_dwordx2 v146, v[114:115], s[100:101]
	v_pk_mul_f32 v[118:119], v[118:119], v[148:149]
	v_pk_mul_f32 v[120:121], v[120:121], v[148:149]
	v_pk_mul_f32 v[118:119], v[118:119], v[6:7]
	v_pk_mul_f32 v[120:121], v[120:121], v[8:9]
	v_cvt_pk_bf16_f32 v118, v118, v119
	v_cvt_pk_bf16_f32 v119, v120, v121
	global_store_dwordx2 v146, v[118:119], s[100:101] offset:512
	v_pk_mul_f32 v[122:123], v[122:123], v[148:149]
	v_pk_mul_f32 v[124:125], v[124:125], v[148:149]
	v_pk_mul_f32 v[122:123], v[122:123], v[10:11]
	v_pk_mul_f32 v[124:125], v[124:125], v[12:13]
	v_cvt_pk_bf16_f32 v122, v122, v123
	v_cvt_pk_bf16_f32 v123, v124, v125
	global_store_dwordx2 v146, v[122:123], s[100:101] offset:1024
	v_pk_mul_f32 v[126:127], v[126:127], v[148:149]
	v_pk_mul_f32 v[128:129], v[128:129], v[148:149]
	v_pk_mul_f32 v[126:127], v[126:127], v[14:15]
	v_pk_mul_f32 v[128:129], v[128:129], v[16:17]
	v_cvt_pk_bf16_f32 v126, v126, v127
	v_cvt_pk_bf16_f32 v127, v128, v129
	global_store_dwordx2 v146, v[126:127], s[100:101] offset:1536
	s_add_u32 s100, s100, 0x400000
	s_addc_u32 s101, s101, 0
	s_waitcnt vmcnt(28)
	v_mul_f32_e32 v147, v130, v130
	v_mul_f32_e32 v148, v131, v131
	v_fmac_f32_e32 v147, v132, v132
	v_fmac_f32_e32 v148, v133, v133
	v_fmac_f32_e32 v147, v134, v134
	v_fmac_f32_e32 v148, v135, v135
	v_fmac_f32_e32 v147, v136, v136
	v_fmac_f32_e32 v148, v137, v137
	v_fmac_f32_e32 v147, v138, v138
	v_fmac_f32_e32 v148, v139, v139
	v_fmac_f32_e32 v147, v140, v140
	v_fmac_f32_e32 v148, v141, v141
	v_fmac_f32_e32 v147, v142, v142
	v_fmac_f32_e32 v148, v143, v143
	v_fmac_f32_e32 v147, v144, v144
	v_fmac_f32_e32 v148, v145, v145
	v_add_f32_e32 v147, v147, v148
	s_nop 1
	v_add_f32_dpp v147, v147, v147 row_shr:1 row_mask:0xf bank_mask:0xf bound_ctrl:1
	s_nop 1
	v_add_f32_dpp v147, v147, v147 row_shr:2 row_mask:0xf bank_mask:0xf bound_ctrl:1
	s_nop 1
	v_add_f32_dpp v147, v147, v147 row_shr:4 row_mask:0xf bank_mask:0xf bound_ctrl:1
	s_nop 1
	v_add_f32_dpp v147, v147, v147 row_shr:8 row_mask:0xf bank_mask:0xf bound_ctrl:1
	v_mov_b32_e32 v148, v1
	s_nop 1
	v_mov_b32_dpp v148, v147 row_bcast:15 row_mask:0xa bank_mask:0xf
	v_add_f32_e32 v147, v147, v148
	v_mov_b32_e32 v148, v1
	s_nop 1
	v_mov_b32_dpp v148, v147 row_bcast:31 row_mask:0xc bank_mask:0xf
	v_add_f32_e32 v147, v147, v148
	s_nop 1
	v_readlane_b32 s4, v147, 63
	s_nop 3
	v_fma_f32 v148, s4, v178, v205
	v_rsq_f32_e32 v148, v148
	s_nop 0
	v_mov_b32_e32 v149, v148
	v_pk_mul_f32 v[130:131], v[130:131], v[148:149]
	v_pk_mul_f32 v[132:133], v[132:133], v[148:149]
	v_pk_mul_f32 v[130:131], v[130:131], v[2:3]
	v_pk_mul_f32 v[132:133], v[132:133], v[4:5]
	v_cvt_pk_bf16_f32 v130, v130, v131
	v_cvt_pk_bf16_f32 v131, v132, v133
	global_store_dwordx2 v146, v[130:131], s[100:101]
	v_pk_mul_f32 v[134:135], v[134:135], v[148:149]
	v_pk_mul_f32 v[136:137], v[136:137], v[148:149]
	v_pk_mul_f32 v[134:135], v[134:135], v[6:7]
	v_pk_mul_f32 v[136:137], v[136:137], v[8:9]
	v_cvt_pk_bf16_f32 v134, v134, v135
	v_cvt_pk_bf16_f32 v135, v136, v137
	global_store_dwordx2 v146, v[134:135], s[100:101] offset:512
	v_pk_mul_f32 v[138:139], v[138:139], v[148:149]
	v_pk_mul_f32 v[140:141], v[140:141], v[148:149]
	v_pk_mul_f32 v[138:139], v[138:139], v[10:11]
	v_pk_mul_f32 v[140:141], v[140:141], v[12:13]
	v_cvt_pk_bf16_f32 v138, v138, v139
	v_cvt_pk_bf16_f32 v139, v140, v141
	global_store_dwordx2 v146, v[138:139], s[100:101] offset:1024
	v_pk_mul_f32 v[142:143], v[142:143], v[148:149]
	v_pk_mul_f32 v[144:145], v[144:145], v[148:149]
	v_pk_mul_f32 v[142:143], v[142:143], v[14:15]
	v_pk_mul_f32 v[144:145], v[144:145], v[16:17]
	v_cvt_pk_bf16_f32 v142, v142, v143
	v_cvt_pk_bf16_f32 v143, v144, v145
	global_store_dwordx2 v146, v[142:143], s[100:101] offset:1536
	s_add_u32 s100, s100, 0x400000
	s_addc_u32 s101, s101, 0
